# row passes: waves 4-7 start ~1.3 us later (s_sleep 12) so the two waves of a SIMD interleave load and compute phases; on top of the peeled K step
# speedup vs baseline: 1.0151x; 1.0017x over previous
.LBB0_904:
	s_or_b64 exec, exec, s[0:1]
	s_lshl_b32 s18, s18, 10
	s_waitcnt lgkmcnt(0)
	v_mov_b32_e32 v0, v213
	v_readlane_b32 s2, v253, 0
	s_barrier
	s_lshl_b64 s[0:1], s[18:19], 2
	v_readlane_b32 s3, v253, 1
	s_add_u32 s4, s58, s0
	v_and_b32_e32 v116, 63, v0
	v_cndmask_b32_e64 v0, 0, 1, s[2:3]
	s_addc_u32 s5, s59, s1
	v_cmp_ne_u32_e64 s[44:45], 1, v0
	s_andn2_b64 vcc, exec, s[2:3]
	v_lshlrev_b32_e32 v2, 4, v116
	v_cmp_eq_u32_e64 s[42:43], 0, v116
	v_lshlrev_b32_e32 v0, 3, v116
	s_cbranch_vccnz .LBB0_1006
	v_readlane_b32 s2, v253, 30
	v_mov_b32_e32 v1, v3
	v_readlane_b32 s3, v253, 31
	v_readlane_b32 s8, v254, 19
	v_lshl_add_u64 v[68:69], s[4:5], 0, v[2:3]
	v_lshl_add_u64 v[74:75], s[2:3], 0, v[0:1]
	v_readlane_b32 s2, v254, 23
	v_readlane_b32 s3, v254, 24
	v_lshl_add_u64 v[70:71], s[68:69], 0, v[2:3]
	v_lshl_add_u64 v[72:73], s[82:83], 0, v[0:1]
	v_lshl_add_u64 v[76:77], s[2:3], 0, v[0:1]
	v_readlane_b32 s2, v254, 29
	v_readlane_b32 s3, v254, 30
	v_readlane_b32 s9, v254, 20
	v_readlane_b32 s10, v254, 27
	v_lshl_add_u64 v[78:79], s[2:3], 0, v[2:3]
	v_readlane_b32 s11, v254, 28
	v_readfirstlane_b32 s2, v213
	s_nop 3
	s_bfe_u32 s2, s2, 0x30006
	s_cmp_lt_u32 s2, 4
	s_cbranch_scc1 .Lstag0
	s_sleep 12
.Lstag0:
	s_branch .LBB0_908
.LBB0_906:
	s_or_b64 exec, exec, s[2:3]

.LBB0_1239:
	s_or_b64 exec, exec, s[2:3]
	s_add_u32 s4, s62, s0
	s_addc_u32 s5, s63, s1
	s_bfe_i64 s[0:1], s[18:19], 0x200000
	s_lshl_b64 s[0:1], s[0:1], 2
	s_add_u32 s0, s56, s0
	s_addc_u32 s1, s57, s1
	s_add_u32 s2, s0, 0x1000
	s_addc_u32 s3, s1, 0
	s_waitcnt lgkmcnt(0)
	v_mov_b32_e32 v0, v213
	s_barrier
	s_and_b64 s[0:1], s[6:7], exec
	s_cselect_b32 s1, 0, s3
	v_and_b32_e32 v116, 63, v0
	s_cselect_b32 s0, 0, s2
	s_and_b64 vcc, exec, s[44:45]
	v_lshlrev_b32_e32 v2, 4, v116
	v_cmp_eq_u32_e64 s[38:39], 0, v116
	v_lshlrev_b32_e32 v0, 3, v116
	v_readlane_b32 s18, v255, 32
	s_cbranch_vccnz .LBB0_1341
	v_readlane_b32 s2, v253, 30
	v_mov_b32_e32 v1, v3
	v_readlane_b32 s3, v253, 31
	s_cmp_lg_u64 s[0:1], 0
	v_readlane_b32 s8, v254, 19
	v_lshl_add_u64 v[74:75], s[2:3], 0, v[0:1]
	v_readlane_b32 s2, v254, 23
	v_readlane_b32 s3, v254, 24
	v_lshl_add_u64 v[68:69], s[4:5], 0, v[2:3]
	s_cselect_b64 s[6:7], -1, 0
	v_lshl_add_u64 v[76:77], s[2:3], 0, v[0:1]
	v_readlane_b32 s2, v254, 29
	v_readlane_b32 s3, v254, 30
	v_lshl_add_u64 v[70:71], s[68:69], 0, v[2:3]
	v_lshl_add_u64 v[72:73], s[82:83], 0, v[0:1]
	v_lshl_add_u64 v[78:79], s[2:3], 0, v[2:3]
	v_readlane_b32 s9, v254, 20
	v_readlane_b32 s10, v254, 27
	v_readlane_b32 s11, v254, 28
	v_readfirstlane_b32 s2, v213
	s_nop 3
	s_bfe_u32 s2, s2, 0x30006
	s_cmp_lt_u32 s2, 4
	s_cbranch_scc1 .Lstag1
	s_sleep 12
.Lstag1:
	s_branch .LBB0_1243
.LBB0_1241:
	s_or_b64 exec, exec, s[2:3]
